# P0 weight conversion (gain variants): 16 W loads + 16 gain loads of a staging step issued together with own registers instead of one memory round trip per element
# speedup vs baseline: 1.0177x; 1.0129x over previous
; __device__ __forceinline__ void conv_item(const float* W, int K, int N, bf16* WT, const float* gain, int mapmode, bool f16, LAS float* scr, int item, int lane) {
;     ...
; #pragma unroll 16
;     for (int i = 0; i < 32; ++i) { const int kk = 2 * i + (lane >> 5); float v = __builtin_nontemporal_load(W + (size_t)(k0 + kk) * N + n0 + (lane & 31)); if (gain) v *= gain[k0 + kk]; scr[kk * 33 + (lane & 31)] = v; }
;     asm volatile("s_waitcnt lgkmcnt(0)" ::: "memory");
.LBB0_10:
	s_add_i32 s29, s29, 32
	s_waitcnt vmcnt(0)
	ds_write_b32 v23, v170 offset:3960
	v_add_u32_e32 v23, 0x1080, v23
	s_cmp_eq_u32 s29, 64
	v_lshl_add_u64 v[24:25], v[24:25], 0, s[8:9]
	s_cbranch_scc1 .LBB0_8
.LBB0_11:
	v_add_u32_e32 v26, s29, v22
	v_mad_i64_i32 v[28:29], s[40:41], v26, s23, v[20:21]
	global_load_dword v28, v[28:29], off nt
	v_ashrrev_i32_e32 v27, 31, v26
	v_add_u32_e32 v33, 2, v26
	v_mad_i64_i32 v[36:37], s[40:41], v33, s23, v[20:21]
	global_load_dword v33, v[36:37], off nt
	v_add_u32_e32 v40, 4, v26
	v_mad_i64_i32 v[40:41], s[40:41], v40, s23, v[20:21]
	global_load_dword v40, v[40:41], off nt
	v_add_u32_e32 v43, 6, v26
	v_mad_i64_i32 v[66:67], s[40:41], v43, s23, v[20:21]
	global_load_dword v43, v[66:67], off nt
	v_add_u32_e32 v70, 8, v26
	v_mad_i64_i32 v[70:71], s[40:41], v70, s23, v[20:21]
	global_load_dword v70, v[70:71], off nt
	v_add_u32_e32 v73, 10, v26
	v_mad_i64_i32 v[76:77], s[40:41], v73, s23, v[20:21]
	global_load_dword v73, v[76:77], off nt
	v_add_u32_e32 v80, 12, v26
	v_mad_i64_i32 v[80:81], s[40:41], v80, s23, v[20:21]
	global_load_dword v80, v[80:81], off nt
	v_add_u32_e32 v117, 14, v26
	v_mad_i64_i32 v[98:99], s[40:41], v117, s23, v[20:21]
	global_load_dword v117, v[98:99], off nt
	v_add_u32_e32 v120, 16, v26
	v_mad_i64_i32 v[120:121], s[40:41], v120, s23, v[20:21]
	global_load_dword v120, v[120:121], off nt
	v_add_u32_e32 v123, 18, v26
	v_mad_i64_i32 v[126:127], s[40:41], v123, s23, v[20:21]
	global_load_dword v123, v[126:127], off nt
	v_add_u32_e32 v130, 20, v26
	v_mad_i64_i32 v[130:131], s[40:41], v130, s23, v[20:21]
	global_load_dword v130, v[130:131], off nt
	v_add_u32_e32 v149, 22, v26
	v_mad_i64_i32 v[152:153], s[40:41], v149, s23, v[20:21]
	global_load_dword v149, v[152:153], off nt
	v_add_u32_e32 v156, 24, v26
	v_mad_i64_i32 v[156:157], s[40:41], v156, s23, v[20:21]
	global_load_dword v156, v[156:157], off nt
	v_add_u32_e32 v159, 26, v26
	v_mad_i64_i32 v[164:165], s[40:41], v159, s23, v[20:21]
	global_load_dword v159, v[164:165], off nt
	v_add_u32_e32 v168, 28, v26
	v_mad_i64_i32 v[168:169], s[40:41], v168, s23, v[20:21]
	global_load_dword v168, v[168:169], off nt
	v_add_u32_e32 v170, 30, v26
	v_mad_i64_i32 v[170:171], s[40:41], v170, s23, v[20:21]
	global_load_dword v170, v[170:171], off nt
	s_and_b64 vcc, exec, s[4:5]
	s_cbranch_vccnz .Lp0g0_ng
	v_lshl_add_u64 v[30:31], v[26:27], 2, s[16:17]
	global_load_dword v27, v[30:31], off
	global_load_dword v34, v[24:25], off offset:-112
	global_load_dword v39, v[24:25], off offset:-104
	global_load_dword v44, v[24:25], off offset:-96
	global_load_dword v69, v[24:25], off offset:-88
	global_load_dword v74, v[24:25], off offset:-80
	global_load_dword v79, v[24:25], off offset:-72
	global_load_dword v118, v[24:25], off offset:-64
	global_load_dword v119, v[24:25], off offset:-56
	global_load_dword v124, v[24:25], off offset:-48
	global_load_dword v129, v[24:25], off offset:-40
	global_load_dword v150, v[24:25], off offset:-32
	global_load_dword v155, v[24:25], off offset:-24
	global_load_dword v160, v[24:25], off offset:-16
	global_load_dword v167, v[24:25], off offset:-8
	global_load_dword v171, v[24:25], off
	s_waitcnt vmcnt(0)
	v_mul_f32_e32 v28, v28, v27
	v_mul_f32_e32 v33, v33, v34
	v_mul_f32_e32 v40, v40, v39
	v_mul_f32_e32 v43, v43, v44
	v_mul_f32_e32 v70, v70, v69
	v_mul_f32_e32 v73, v73, v74
	v_mul_f32_e32 v80, v80, v79
	v_mul_f32_e32 v117, v117, v118
	v_mul_f32_e32 v120, v120, v119
	v_mul_f32_e32 v123, v123, v124
	v_mul_f32_e32 v130, v130, v129
	v_mul_f32_e32 v149, v149, v150
	v_mul_f32_e32 v156, v156, v155
	v_mul_f32_e32 v159, v159, v160
	v_mul_f32_e32 v168, v168, v167
	v_mul_f32_e32 v170, v170, v171
.Lp0g0_ng:
	s_waitcnt vmcnt(0)
	ds_write_b32 v23, v28
	ds_write_b32 v23, v33 offset:264
	ds_write_b32 v23, v40 offset:528
	ds_write_b32 v23, v43 offset:792
	ds_write_b32 v23, v70 offset:1056
	ds_write_b32 v23, v73 offset:1320
	ds_write_b32 v23, v80 offset:1584
	ds_write_b32 v23, v117 offset:1848
	ds_write_b32 v23, v120 offset:2112
	ds_write_b32 v23, v123 offset:2376
	ds_write_b32 v23, v130 offset:2640
	ds_write_b32 v23, v149 offset:2904
	ds_write_b32 v23, v156 offset:3168
	ds_write_b32 v23, v159 offset:3432
	ds_write_b32 v23, v168 offset:3696
	s_branch .LBB0_10

; __device__ __forceinline__ void conv_item(const float* W, int K, int N, bf16* WT, const float* gain, int mapmode, bool f16, LAS float* scr, int item, int lane) {
;     ...
; #pragma unroll 16
;     for (int i = 0; i < 32; ++i) { const int kk = 2 * i + (lane >> 5); float v = __builtin_nontemporal_load(W + (size_t)(k0 + kk) * N + n0 + (lane & 31)); if (gain) v *= gain[k0 + kk]; scr[kk * 33 + (lane & 31)] = v; }
;     asm volatile("s_waitcnt lgkmcnt(0)" ::: "memory");
.LBB0_64:
	s_add_i32 s29, s29, 32
	s_add_u32 s36, s36, 0x80
	s_addc_u32 s37, s37, 0
	s_waitcnt vmcnt(0)
	ds_write_b32 v25, v180 offset:3960
	s_cmp_eq_u32 s29, 64
	v_add_u32_e32 v25, 0x1080, v25
	s_cbranch_scc1 .LBB0_62
.LBB0_65:
	v_add_u32_e32 v28, s29, v24
	v_ashrrev_i32_e32 v29, 31, v28
	v_lshlrev_b64 v[30:31], 11, v[28:29]
	v_lshl_add_u64 v[30:31], v[22:23], 0, v[30:31]
	global_load_dword v30, v[30:31], off nt
	v_add_u32_e32 v40, 2, v28
	v_ashrrev_i32_e32 v41, 31, v40
	v_lshlrev_b64 v[40:41], 11, v[40:41]
	v_lshl_add_u64 v[40:41], v[22:23], 0, v[40:41]
	global_load_dword v37, v[40:41], off nt
	v_lshl_add_u64 v[38:39], s[36:37], 0, v[26:27]
	v_add_u32_e32 v44, 4, v28
	v_ashrrev_i32_e32 v45, 31, v44
	v_lshlrev_b64 v[44:45], 11, v[44:45]
	v_lshl_add_u64 v[44:45], v[22:23], 0, v[44:45]
	global_load_dword v44, v[44:45], off nt
	v_add_u32_e32 v116, 6, v28
	v_ashrrev_i32_e32 v117, 31, v116
	v_lshlrev_b64 v[116:117], 11, v[116:117]
	v_lshl_add_u64 v[116:117], v[22:23], 0, v[116:117]
	global_load_dword v99, v[116:117], off nt
	v_add_u32_e32 v120, 8, v28
	v_ashrrev_i32_e32 v121, 31, v120
	v_lshlrev_b64 v[120:121], 11, v[120:121]
	v_lshl_add_u64 v[120:121], v[22:23], 0, v[120:121]
	global_load_dword v120, v[120:121], off nt
	v_add_u32_e32 v124, 10, v28
	v_ashrrev_i32_e32 v125, 31, v124
	v_lshlrev_b64 v[124:125], 11, v[124:125]
	v_lshl_add_u64 v[124:125], v[22:23], 0, v[124:125]
	global_load_dword v123, v[124:125], off nt
	v_add_u32_e32 v128, 12, v28
	v_ashrrev_i32_e32 v129, 31, v128
	v_lshlrev_b64 v[128:129], 11, v[128:129]
	v_lshl_add_u64 v[128:129], v[22:23], 0, v[128:129]
	global_load_dword v128, v[128:129], off nt
	v_add_u32_e32 v148, 14, v28
	v_ashrrev_i32_e32 v149, 31, v148
	v_lshlrev_b64 v[148:149], 11, v[148:149]
	v_lshl_add_u64 v[148:149], v[22:23], 0, v[148:149]
	global_load_dword v131, v[148:149], off nt
	v_add_u32_e32 v152, 16, v28
	v_ashrrev_i32_e32 v153, 31, v152
	v_lshlrev_b64 v[152:153], 11, v[152:153]
	v_lshl_add_u64 v[152:153], v[22:23], 0, v[152:153]
	global_load_dword v152, v[152:153], off nt
	v_add_u32_e32 v156, 18, v28
	v_ashrrev_i32_e32 v157, 31, v156
	v_lshlrev_b64 v[156:157], 11, v[156:157]
	v_lshl_add_u64 v[156:157], v[22:23], 0, v[156:157]
	global_load_dword v155, v[156:157], off nt
	v_add_u32_e32 v160, 20, v28
	v_ashrrev_i32_e32 v161, 31, v160
	v_lshlrev_b64 v[160:161], 11, v[160:161]
	v_lshl_add_u64 v[160:161], v[22:23], 0, v[160:161]
	global_load_dword v160, v[160:161], off nt
	v_add_u32_e32 v166, 22, v28
	v_ashrrev_i32_e32 v167, 31, v166
	v_lshlrev_b64 v[166:167], 11, v[166:167]
	v_lshl_add_u64 v[166:167], v[22:23], 0, v[166:167]
	global_load_dword v165, v[166:167], off nt
	v_add_u32_e32 v170, 24, v28
	v_ashrrev_i32_e32 v171, 31, v170
	v_lshlrev_b64 v[170:171], 11, v[170:171]
	v_lshl_add_u64 v[170:171], v[22:23], 0, v[170:171]
	global_load_dword v170, v[170:171], off nt
	v_add_u32_e32 v174, 26, v28
	v_ashrrev_i32_e32 v175, 31, v174
	v_lshlrev_b64 v[174:175], 11, v[174:175]
	v_lshl_add_u64 v[174:175], v[22:23], 0, v[174:175]
	global_load_dword v173, v[174:175], off nt
	v_add_u32_e32 v178, 28, v28
	v_ashrrev_i32_e32 v179, 31, v178
	v_lshlrev_b64 v[178:179], 11, v[178:179]
	v_lshl_add_u64 v[178:179], v[22:23], 0, v[178:179]
	global_load_dword v178, v[178:179], off nt
	v_add_u32_e32 v180, 30, v28
	v_ashrrev_i32_e32 v181, 31, v180
	v_lshlrev_b64 v[180:181], 11, v[180:181]
	v_lshl_add_u64 v[180:181], v[22:23], 0, v[180:181]
	global_load_dword v180, v[180:181], off nt
	s_and_b64 vcc, exec, s[4:5]
	s_cbranch_vccnz .Lp0g1_ng
	v_lshl_add_u64 v[32:33], v[28:29], 2, s[16:17]
	global_load_dword v29, v[32:33], off
	global_load_dword v40, v[38:39], off offset:-112
	global_load_dword v43, v[38:39], off offset:-104
	global_load_dword v36, v[38:39], off offset:-96
	global_load_dword v119, v[38:39], off offset:-88
	global_load_dword v42, v[38:39], off offset:-80
	global_load_dword v127, v[38:39], off offset:-72
	global_load_dword v98, v[38:39], off offset:-64
	global_load_dword v151, v[38:39], off offset:-56
	global_load_dword v118, v[38:39], off offset:-48
	global_load_dword v159, v[38:39], off offset:-40
	global_load_dword v122, v[38:39], off offset:-32
	global_load_dword v169, v[38:39], off offset:-24
	global_load_dword v126, v[38:39], off offset:-16
	global_load_dword v177, v[38:39], off offset:-8
	global_load_dword v181, v[38:39], off
	s_waitcnt vmcnt(0)
	v_mul_f32_e32 v30, v30, v29
	v_mul_f32_e32 v37, v37, v40
	v_mul_f32_e32 v44, v44, v43
	v_mul_f32_e32 v99, v99, v36
	v_mul_f32_e32 v120, v120, v119
	v_mul_f32_e32 v123, v123, v42
	v_mul_f32_e32 v128, v128, v127
	v_mul_f32_e32 v131, v131, v98
	v_mul_f32_e32 v152, v152, v151
	v_mul_f32_e32 v155, v155, v118
	v_mul_f32_e32 v160, v160, v159
	v_mul_f32_e32 v165, v165, v122
	v_mul_f32_e32 v170, v170, v169
	v_mul_f32_e32 v173, v173, v126
	v_mul_f32_e32 v178, v178, v177
	v_mul_f32_e32 v180, v180, v181
.Lp0g1_ng:
	s_waitcnt vmcnt(0)
	ds_write_b32 v25, v30
	ds_write_b32 v25, v37 offset:264
	ds_write_b32 v25, v44 offset:528
	ds_write_b32 v25, v99 offset:792
	ds_write_b32 v25, v120 offset:1056
	ds_write_b32 v25, v123 offset:1320
	ds_write_b32 v25, v128 offset:1584
	ds_write_b32 v25, v131 offset:1848
	ds_write_b32 v25, v152 offset:2112
	ds_write_b32 v25, v155 offset:2376
	ds_write_b32 v25, v160 offset:2640
	ds_write_b32 v25, v165 offset:2904
	ds_write_b32 v25, v170 offset:3168
	ds_write_b32 v25, v173 offset:3432
	ds_write_b32 v25, v178 offset:3696
	s_branch .LBB0_64

; __device__ __forceinline__ void conv_item(const float* W, int K, int N, bf16* WT, const float* gain, int mapmode, bool f16, LAS float* scr, int item, int lane) {
;     ...
; #pragma unroll 16
;     for (int i = 0; i < 32; ++i) { const int kk = 2 * i + (lane >> 5); float v = __builtin_nontemporal_load(W + (size_t)(k0 + kk) * N + n0 + (lane & 31)); if (gain) v *= gain[k0 + kk]; scr[kk * 33 + (lane & 31)] = v; }
;     asm volatile("s_waitcnt lgkmcnt(0)" ::: "memory");
.LBB0_102:
	v_add_u32_e32 v28, s29, v24
	v_ashrrev_i32_e32 v29, 31, v28
	v_lshlrev_b64 v[30:31], 12, v[28:29]
	v_lshl_add_u64 v[30:31], v[22:23], 0, v[30:31]
	global_load_dword v30, v[30:31], off nt
	v_cndmask_b32_e64 v31, 0, 1, s[16:17]
	v_cmp_ne_u32_e64 s[4:5], 1, v31
	v_add_u32_e32 v40, 2, v28
	v_ashrrev_i32_e32 v41, 31, v40
	v_lshlrev_b64 v[40:41], 12, v[40:41]
	v_lshl_add_u64 v[40:41], v[22:23], 0, v[40:41]
	global_load_dword v37, v[40:41], off nt
	v_lshl_add_u64 v[38:39], s[36:37], 0, v[26:27]
	v_add_u32_e32 v44, 4, v28
	v_ashrrev_i32_e32 v45, 31, v44
	v_lshlrev_b64 v[44:45], 12, v[44:45]
	v_lshl_add_u64 v[44:45], v[22:23], 0, v[44:45]
	global_load_dword v44, v[44:45], off nt
	v_add_u32_e32 v116, 6, v28
	v_ashrrev_i32_e32 v117, 31, v116
	v_lshlrev_b64 v[116:117], 12, v[116:117]
	v_lshl_add_u64 v[116:117], v[22:23], 0, v[116:117]
	global_load_dword v99, v[116:117], off nt
	v_add_u32_e32 v120, 8, v28
	v_ashrrev_i32_e32 v121, 31, v120
	v_lshlrev_b64 v[120:121], 12, v[120:121]
	v_lshl_add_u64 v[120:121], v[22:23], 0, v[120:121]
	global_load_dword v120, v[120:121], off nt
	v_add_u32_e32 v124, 10, v28
	v_ashrrev_i32_e32 v125, 31, v124
	v_lshlrev_b64 v[124:125], 12, v[124:125]
	v_lshl_add_u64 v[124:125], v[22:23], 0, v[124:125]
	global_load_dword v123, v[124:125], off nt
	v_add_u32_e32 v128, 12, v28
	v_ashrrev_i32_e32 v129, 31, v128
	v_lshlrev_b64 v[128:129], 12, v[128:129]
	v_lshl_add_u64 v[128:129], v[22:23], 0, v[128:129]
	global_load_dword v128, v[128:129], off nt
	v_add_u32_e32 v148, 14, v28
	v_ashrrev_i32_e32 v149, 31, v148
	v_lshlrev_b64 v[148:149], 12, v[148:149]
	v_lshl_add_u64 v[148:149], v[22:23], 0, v[148:149]
	global_load_dword v131, v[148:149], off nt
	v_add_u32_e32 v152, 16, v28
	v_ashrrev_i32_e32 v153, 31, v152
	v_lshlrev_b64 v[152:153], 12, v[152:153]
	v_lshl_add_u64 v[152:153], v[22:23], 0, v[152:153]
	global_load_dword v152, v[152:153], off nt
	v_add_u32_e32 v156, 18, v28
	v_ashrrev_i32_e32 v157, 31, v156
	v_lshlrev_b64 v[156:157], 12, v[156:157]
	v_lshl_add_u64 v[156:157], v[22:23], 0, v[156:157]
	global_load_dword v155, v[156:157], off nt
	v_add_u32_e32 v160, 20, v28
	v_ashrrev_i32_e32 v161, 31, v160
	v_lshlrev_b64 v[160:161], 12, v[160:161]
	v_lshl_add_u64 v[160:161], v[22:23], 0, v[160:161]
	global_load_dword v160, v[160:161], off nt
	v_add_u32_e32 v166, 22, v28
	v_ashrrev_i32_e32 v167, 31, v166
	v_lshlrev_b64 v[166:167], 12, v[166:167]
	v_lshl_add_u64 v[166:167], v[22:23], 0, v[166:167]
	global_load_dword v165, v[166:167], off nt
	v_add_u32_e32 v170, 24, v28
	v_ashrrev_i32_e32 v171, 31, v170
	v_lshlrev_b64 v[170:171], 12, v[170:171]
	v_lshl_add_u64 v[170:171], v[22:23], 0, v[170:171]
	global_load_dword v170, v[170:171], off nt
	v_add_u32_e32 v174, 26, v28
	v_ashrrev_i32_e32 v175, 31, v174
	v_lshlrev_b64 v[174:175], 12, v[174:175]
	v_lshl_add_u64 v[174:175], v[22:23], 0, v[174:175]
	global_load_dword v173, v[174:175], off nt
	v_add_u32_e32 v178, 28, v28
	v_ashrrev_i32_e32 v179, 31, v178
	v_lshlrev_b64 v[178:179], 12, v[178:179]
	v_lshl_add_u64 v[178:179], v[22:23], 0, v[178:179]
	global_load_dword v178, v[178:179], off nt
	v_add_u32_e32 v180, 30, v28
	v_ashrrev_i32_e32 v181, 31, v180
	v_lshlrev_b64 v[180:181], 12, v[180:181]
	v_lshl_add_u64 v[180:181], v[22:23], 0, v[180:181]
	global_load_dword v180, v[180:181], off nt
	s_andn2_b64 vcc, exec, s[16:17]
	s_cbranch_vccnz .Lp0g2_ng
	v_lshl_add_u64 v[32:33], v[28:29], 2, s[12:13]
	global_load_dword v29, v[32:33], off
	global_load_dword v40, v[38:39], off offset:-112
	global_load_dword v43, v[38:39], off offset:-104
	global_load_dword v36, v[38:39], off offset:-96
	global_load_dword v119, v[38:39], off offset:-88
	global_load_dword v42, v[38:39], off offset:-80
	global_load_dword v127, v[38:39], off offset:-72
	global_load_dword v98, v[38:39], off offset:-64
	global_load_dword v151, v[38:39], off offset:-56
	global_load_dword v118, v[38:39], off offset:-48
	global_load_dword v159, v[38:39], off offset:-40
	global_load_dword v122, v[38:39], off offset:-32
	global_load_dword v169, v[38:39], off offset:-24
	global_load_dword v126, v[38:39], off offset:-16
	global_load_dword v177, v[38:39], off offset:-8
	global_load_dword v181, v[38:39], off
	s_waitcnt vmcnt(0)
	v_mul_f32_e32 v30, v30, v29
	v_mul_f32_e32 v37, v37, v40
	v_mul_f32_e32 v44, v44, v43
	v_mul_f32_e32 v99, v99, v36
	v_mul_f32_e32 v120, v120, v119
	v_mul_f32_e32 v123, v123, v42
	v_mul_f32_e32 v128, v128, v127
	v_mul_f32_e32 v131, v131, v98
	v_mul_f32_e32 v152, v152, v151
	v_mul_f32_e32 v155, v155, v118
	v_mul_f32_e32 v160, v160, v159
	v_mul_f32_e32 v165, v165, v122
	v_mul_f32_e32 v170, v170, v169
	v_mul_f32_e32 v173, v173, v126
	v_mul_f32_e32 v178, v178, v177
	v_mul_f32_e32 v180, v180, v181

; __device__ __forceinline__ void conv_item(const float* W, int K, int N, bf16* WT, const float* gain, int mapmode, bool f16, LAS float* scr, int item, int lane) {
;     ...
; #pragma unroll 16
;     for (int i = 0; i < 32; ++i) { const int kk = 2 * i + (lane >> 5); float v = __builtin_nontemporal_load(W + (size_t)(k0 + kk) * N + n0 + (lane & 31)); if (gain) v *= gain[k0 + kk]; scr[kk * 33 + (lane & 31)] = v; }
;     asm volatile("s_waitcnt lgkmcnt(0)" ::: "memory");
.LBB0_143:
	s_add_u32 s30, s30, 0xb0000
	s_addc_u32 s31, s31, 0
	s_add_u32 s36, s36, 0x80
	s_addc_u32 s37, s37, 0
	s_waitcnt vmcnt(0)
	ds_write_b32 v83, v160 offset:3960
	s_cmp_eq_u32 s30, 0x160000
	v_add_u32_e32 v83, 0x1080, v83
	s_cbranch_scc1 .LBB0_176
.LBB0_144:
	v_lshl_add_u64 v[58:59], v[54:55], 0, s[30:31]
	global_load_dword v58, v[58:59], off nt
	v_cndmask_b32_e64 v59, 0, 1, s[12:13]
	v_cmp_ne_u32_e64 s[4:5], 1, v59
	v_lshl_add_u64 v[116:117], v[52:53], 0, s[30:31]
	global_load_dword v116, v[116:117], off nt
	v_lshl_add_u64 v[98:99], s[36:37], 0, v[24:25]
	v_lshl_add_u64 v[120:121], v[50:51], 0, s[30:31]
	global_load_dword v119, v[120:121], off nt
	v_lshl_add_u64 v[124:125], v[48:49], 0, s[30:31]
	global_load_dword v122, v[124:125], off nt
	v_lshl_add_u64 v[128:129], v[46:47], 0, s[30:31]
	global_load_dword v127, v[128:129], off nt
	v_lshl_add_u64 v[150:151], v[44:45], 0, s[30:31]
	global_load_dword v148, v[150:151], off nt
	v_lshl_add_u64 v[154:155], v[42:43], 0, s[30:31]
	global_load_dword v153, v[154:155], off nt
	v_lshl_add_u64 v[158:159], v[40:41], 0, s[30:31]
	global_load_dword v156, v[158:159], off nt
	v_lshl_add_u64 v[166:167], v[38:39], 0, s[30:31]
	global_load_dword v165, v[166:167], off nt
	v_lshl_add_u64 v[170:171], v[36:37], 0, s[30:31]
	global_load_dword v168, v[170:171], off nt
	v_lshl_add_u64 v[174:175], v[34:35], 0, s[30:31]
	global_load_dword v173, v[174:175], off nt
	v_lshl_add_u64 v[178:179], v[32:33], 0, s[30:31]
	global_load_dword v176, v[178:179], off nt
	v_lshl_add_u64 v[182:183], v[30:31], 0, s[30:31]
	global_load_dword v181, v[182:183], off nt
	v_lshl_add_u64 v[186:187], v[28:29], 0, s[30:31]
	global_load_dword v184, v[186:187], off nt
	v_lshl_add_u64 v[190:191], v[26:27], 0, s[30:31]
	global_load_dword v189, v[190:191], off nt
	v_lshl_add_u64 v[192:193], v[22:23], 0, s[30:31]
	global_load_dword v160, v[192:193], off nt
	s_andn2_b64 vcc, exec, s[12:13]
	s_cbranch_vccnz .Lp0g3_ng
	v_lshl_add_u64 v[84:85], s[36:37], 0, v[56:57]
	global_load_dword v59, v[84:85], off offset:-120
	global_load_dword v117, v[98:99], off offset:-112
	global_load_dword v118, v[98:99], off offset:-104
	global_load_dword v123, v[98:99], off offset:-96
	global_load_dword v126, v[98:99], off offset:-88
	global_load_dword v149, v[98:99], off offset:-80
	global_load_dword v152, v[98:99], off offset:-72
	global_load_dword v157, v[98:99], off offset:-64
	global_load_dword v164, v[98:99], off offset:-56
	global_load_dword v169, v[98:99], off offset:-48
	global_load_dword v172, v[98:99], off offset:-40
	global_load_dword v177, v[98:99], off offset:-32
	global_load_dword v180, v[98:99], off offset:-24
	global_load_dword v185, v[98:99], off offset:-16
	global_load_dword v188, v[98:99], off offset:-8
	global_load_dword v130, v[98:99], off
	s_waitcnt vmcnt(0)
	v_mul_f32_e32 v58, v58, v59
	v_mul_f32_e32 v116, v116, v117
	v_mul_f32_e32 v119, v119, v118
	v_mul_f32_e32 v122, v122, v123
	v_mul_f32_e32 v127, v127, v126
	v_mul_f32_e32 v148, v148, v149
	v_mul_f32_e32 v153, v153, v152
	v_mul_f32_e32 v156, v156, v157
	v_mul_f32_e32 v165, v165, v164
	v_mul_f32_e32 v168, v168, v169
	v_mul_f32_e32 v173, v173, v172
	v_mul_f32_e32 v176, v176, v177
	v_mul_f32_e32 v181, v181, v180
	v_mul_f32_e32 v184, v184, v185
	v_mul_f32_e32 v189, v189, v188
	v_mul_f32_e32 v160, v160, v130
.Lp0g3_ng:
	s_waitcnt vmcnt(0)
	ds_write_b32 v83, v58
	ds_write_b32 v83, v116 offset:264
	ds_write_b32 v83, v119 offset:528
	ds_write_b32 v83, v122 offset:792
	ds_write_b32 v83, v127 offset:1056
	ds_write_b32 v83, v148 offset:1320
	ds_write_b32 v83, v153 offset:1584
	ds_write_b32 v83, v156 offset:1848
	ds_write_b32 v83, v165 offset:2112
	ds_write_b32 v83, v168 offset:2376
	ds_write_b32 v83, v173 offset:2640
	ds_write_b32 v83, v176 offset:2904
	ds_write_b32 v83, v181 offset:3168
	ds_write_b32 v83, v184 offset:3432
	ds_write_b32 v83, v189 offset:3696
	s_branch .LBB0_143
